# layer-1 weight conversion deferred from P0 into the idle blocks of the last GEMM rounds of P2 (480 tiles), P3 (384) and P5 (448)
# speedup vs baseline: 1.0055x; 1.0055x over previous
.LBB0_20:
	v_lshlrev_b32_e32 v2, 5, v5
	v_and_b32_e32 v5, 0x60, v2
	v_ashrrev_i32_e32 v2, 31, v7
	v_mul_lo_u32 v10, s25, v7
	v_mul_lo_u32 v2, s24, v2
	v_mad_u64_u32 v[8:9], s[24:25], s24, v7, 0
	v_add3_u32 v9, v9, v2, v10
	v_lshlrev_b32_e32 v2, 1, v5
	v_lshlrev_b32_e32 v6, 2, v6
	v_mul_u32_u24_e32 v5, 0x204, v5
	v_lshl_add_u64 v[8:9], v[8:9], 1, s[22:23]
	s_ashr_i32 s29, s28, 31
	v_add3_u32 v5, 0, v6, v5
	v_lshl_add_u64 v[8:9], s[28:29], 1, v[8:9]
	v_add_u32_e32 v10, 0x400, v5
	ds_read2_b32 v[6:7], v5 offset1:129
	ds_read2_b32 v[10:11], v10 offset0:2 offset1:131
	v_add_u32_e32 v12, 0x800, v5
	v_add_u32_e32 v14, 0xc00, v5
	v_lshl_add_u64 v[16:17], v[8:9], 0, v[2:3]
	v_add_u32_e32 v2, 0x1000, v5
	ds_read2_b32 v[12:13], v12 offset0:4 offset1:133
	ds_read2_b32 v[14:15], v14 offset0:6 offset1:135
	s_waitcnt lgkmcnt(3)
	v_cvt_pk_bf16_f32 v6, v6, v7
	s_waitcnt lgkmcnt(2)
	v_cvt_pk_bf16_f32 v7, v10, v11
	s_waitcnt lgkmcnt(1)
	v_cvt_pk_bf16_f32 v8, v12, v13
	s_waitcnt lgkmcnt(0)
	v_cvt_pk_bf16_f32 v9, v14, v15
	ds_read2_b32 v[10:11], v2 offset0:8 offset1:137
	v_add_u32_e32 v2, 0x1400, v5
	ds_read2_b32 v[12:13], v2 offset0:10 offset1:139
	v_add_u32_e32 v2, 0x1800, v5
	ds_read2_b32 v[14:15], v2 offset0:12 offset1:141
	v_add_u32_e32 v2, 0x1c00, v5
	ds_read2_b32 v[18:19], v2 offset0:14 offset1:143
	v_add_u32_e32 v2, 0x2000, v5
	global_store_dwordx4 v[16:17], v[6:9], off
	s_waitcnt lgkmcnt(3)
	v_cvt_pk_bf16_f32 v6, v10, v11
	s_waitcnt lgkmcnt(2)
	v_cvt_pk_bf16_f32 v7, v12, v13
	s_waitcnt lgkmcnt(1)
	v_cvt_pk_bf16_f32 v8, v14, v15
	s_waitcnt lgkmcnt(0)
	v_cvt_pk_bf16_f32 v9, v18, v19
	ds_read2_b32 v[10:11], v2 offset0:16 offset1:145
	v_add_u32_e32 v2, 0x2400, v5
	ds_read2_b32 v[12:13], v2 offset0:18 offset1:147
	v_add_u32_e32 v2, 0x2800, v5
	ds_read2_b32 v[14:15], v2 offset0:20 offset1:149
	v_add_u32_e32 v2, 0x2c00, v5
	ds_read2_b32 v[18:19], v2 offset0:22 offset1:151
	v_add_u32_e32 v2, 0x3000, v5
	global_store_dwordx4 v[16:17], v[6:9], off offset:16
	s_waitcnt lgkmcnt(3)
	s_nop 0
	v_cvt_pk_bf16_f32 v6, v10, v11
	s_waitcnt lgkmcnt(2)
	v_cvt_pk_bf16_f32 v7, v12, v13
	s_waitcnt lgkmcnt(1)
	v_cvt_pk_bf16_f32 v8, v14, v15
	s_waitcnt lgkmcnt(0)
	v_cvt_pk_bf16_f32 v9, v18, v19
	ds_read2_b32 v[10:11], v2 offset0:24 offset1:153
	v_add_u32_e32 v2, 0x3400, v5
	ds_read2_b32 v[12:13], v2 offset0:26 offset1:155
	v_add_u32_e32 v2, 0x3800, v5
	ds_read2_b32 v[14:15], v2 offset0:28 offset1:157
	v_add_u32_e32 v2, 0x3c00, v5
	ds_read2_b32 v[18:19], v2 offset0:30 offset1:159
	global_store_dwordx4 v[16:17], v[6:9], off offset:32
	s_waitcnt lgkmcnt(3)
	s_nop 0
	v_cvt_pk_bf16_f32 v6, v10, v11
	s_waitcnt lgkmcnt(2)
	v_cvt_pk_bf16_f32 v7, v12, v13
	s_waitcnt lgkmcnt(1)
	v_cvt_pk_bf16_f32 v8, v14, v15
	s_waitcnt lgkmcnt(0)
	v_cvt_pk_bf16_f32 v9, v18, v19
	global_store_dwordx4 v[16:17], v[6:9], off offset:48
	s_barrier
	s_add_i32 s92, s92, s90
	s_cmp_lt_i32 s92, s93
	s_cbranch_scc1 .Lmy_cv_head
	s_cmp_eq_u32 s94, 0
	s_cbranch_scc1 .LBB0_52
	s_cmp_eq_u32 s94, 1
	s_cbranch_scc1 .Lmy_cv_ret1
	s_cmp_eq_u32 s94, 2
	s_cbranch_scc1 .Lmy_cv_ret2
	s_branch .Lmy_cv_ret3

.LBB0_232:
	s_waitcnt vmcnt(0)
	s_barrier
	s_cmp_lt_u32 s2, 176
	s_cbranch_scc1 .LBB0_233
	s_mov_b64 s[80:81], s[10:11]
	s_mov_b64 s[82:83], s[12:13]
	s_mov_b64 s[84:85], s[14:15]
	s_mov_b64 s[86:87], s[52:53]
	s_mov_b64 s[88:89], s[54:55]
	s_mov_b64 s[98:99], s[70:71]
	s_mov_b32 s94, 1
	s_movk_i32 s95, 0x2c0
	s_movk_i32 s96, 0x420
	s_movk_i32 s97, 0x500
	s_movk_i32 s93, 480
	s_movk_i32 s90, 80
	s_sub_i32 s92, s2, 176
	s_branch .Lmy_cv_setup
.Lmy_cv_ret1:
	s_mov_b64 s[10:11], s[80:81]
	s_mov_b64 s[12:13], s[82:83]
	s_mov_b64 s[14:15], s[84:85]
	s_mov_b64 s[52:53], s[86:87]
	s_mov_b64 s[54:55], s[88:89]
	s_mov_b64 s[70:71], s[98:99]

.LBB0_371:
	s_waitcnt vmcnt(0)
	s_barrier
	s_cmp_lt_u32 s2, 128
	s_cbranch_scc1 .LBB0_372
	s_mov_b64 s[80:81], s[10:11]
	s_mov_b64 s[82:83], s[12:13]
	s_mov_b64 s[84:85], s[14:15]
	s_mov_b64 s[86:87], s[52:53]
	s_mov_b64 s[88:89], s[54:55]
	s_mov_b64 s[98:99], s[70:71]
	s_mov_b32 s94, 2
	s_movk_i32 s95, 0x2c0
	s_movk_i32 s96, 0x420
	s_movk_i32 s97, 0x500
	s_movk_i32 s93, 864
	s_movk_i32 s90, 128
	s_sub_i32 s92, s2, -352
	s_branch .Lmy_cv_setup

.LBB0_560:
	s_waitcnt vmcnt(0)
	s_barrier
	s_cmp_lt_u32 s2, 32
	s_cbranch_scc1 .LBB0_561
	s_mov_b64 s[80:81], s[10:11]
	s_mov_b64 s[82:83], s[12:13]
	s_mov_b64 s[84:85], s[14:15]
	s_mov_b64 s[86:87], s[52:53]
	s_mov_b64 s[88:89], s[54:55]
	s_mov_b64 s[98:99], s[70:71]
	s_mov_b32 s94, 3
	s_movk_i32 s95, 0x2c0
	s_movk_i32 s96, 0x420
	s_movk_i32 s97, 0x500
	s_movk_i32 s93, 1312
	s_movk_i32 s90, 224
	s_sub_i32 s92, s2, -832
	s_branch .Lmy_cv_setup
